# on top of v60: GEMM phase prologue de-serialised - the six K-tile-1 staging loads are issued together with the eight K-tile-0 loads, first wait becomes a counted vmcnt(8)
# speedup vs baseline: 1.0027x; 1.0016x over previous
.LBB0_215:
	s_add_u32 s9, s34, 0x12c00000
	s_addc_u32 s14, s35, 0
	s_and_b64 s[12:13], s[4:5], exec
	s_cselect_b32 s28, s14, s79
	s_cselect_b32 s61, s9, s78
	s_add_u32 s82, s34, 0x18c00000
	s_addc_u32 s83, s35, 0
	s_and_b64 s[12:13], s[4:5], exec
	s_mov_b32 s9, 0x38000
	s_cselect_b32 s9, s9, 0x16000
	s_add_u32 s36, s85, s9
	s_addc_u32 s37, s88, 0
	s_and_b32 s9, s6, 3
	s_add_i32 m0, s45, 0x18000
	v_lshl_add_u64 v[2:3], v[2:3], 0, s[64:65]
	s_lshl_b32 s71, s7, 6
	s_lshl_b32 s7, s7, 13
	s_lshl_b32 s14, s9, 12
	global_load_lds_dwordx4 v[2:3], off
	s_add_i32 m0, s45, 0x1a000
	s_add_u32 s12, s42, 0x8000
	v_mov_b32_e32 v163, v191
	v_lshl_add_u64 v[2:3], v[4:5], 0, s[64:65]
	s_addc_u32 s13, s43, 0
	s_add_i32 s29, s45, 0x8000
	v_mov_b32_e32 v167, v191
	global_load_lds_dwordx4 v[2:3], off
	v_lshl_add_u64 v[2:3], s[12:13], 0, v[162:163]
	s_mov_b32 m0, s29
	s_add_i32 s21, s45, 0xa000
	global_load_lds_dwordx4 v[2:3], off
	v_lshl_add_u64 v[2:3], s[12:13], 0, v[166:167]
	s_add_u32 s12, s10, 0x40080
	s_mov_b32 m0, s21
	s_addc_u32 s13, s11, 0
	global_load_lds_dwordx4 v[2:3], off
	s_add_i32 m0, s45, 0x1c000
	v_lshl_add_u64 v[2:3], s[12:13], 0, v[164:165]
	global_load_lds_dwordx4 v[2:3], off
	v_lshl_add_u64 v[2:3], s[12:13], 0, v[168:169]
	s_add_i32 m0, s45, 0x1e000
	s_cmpk_lt_u32 s2, 0x100
	global_load_lds_dwordx4 v[2:3], off
	v_bfe_u32 v3, v196, 4, 2
	v_and_b32_e32 v197, 15, v196
	v_lshlrev_b32_e32 v190, 4, v3
	v_lshlrev_b32_e32 v5, 2, v196
	s_cselect_b64 s[12:13], -1, 0
	s_cmp_lg_u32 s71, 64
	s_cbranch_scc1 .Lpro_r
	s_barrier
.Lpro_r:
	s_waitcnt vmcnt(8)
	s_barrier
	s_bfe_u32 s2, s2, 0x10006
	v_lshlrev_b32_e32 v4, 3, v3
	v_lshl_or_b32 v2, v197, 6, v190
	v_and_b32_e32 v5, 32, v5
	s_cmp_eq_u32 s2, 0
	v_mov_b32_e32 v1, 0x3e38aa3b
	v_bitop3_b32 v12, v2, s7, v5 bitop3:0xde
	v_bitop3_b32 v199, s14, v2, v5 bitop3:0xf6
	v_lshl_or_b32 v2, s9, 5, v4
	s_cselect_b64 s[14:15], -1, 0
	v_lshl_or_b32 v4, s2, 5, v4
	s_abs_i32 s2, s49
	v_cndmask_b32_e64 v1, v1, 1.0, s[4:5]
	v_cmp_eq_u32_e32 vcc, 0, v3
	v_cmp_gt_u32_e64 s[4:5], 2, v3
	v_cvt_f32_u32_e32 v3, s2
	v_and_b32_e32 v5, 1, v6
	s_bfe_u32 s72, s6, 0x10001
	s_sub_i32 s6, 0, s2
	v_rcp_iflag_f32_e32 v3, v3
	s_waitcnt vmcnt(6)
	v_writelane_b32 v255, s85, 57
	v_cndmask_b32_e64 v170, 1.0, -1.0, vcc
	v_mul_f32_e32 v3, 0x4f7ffffe, v3
	v_cvt_u32_f32_e32 v3, v3
	v_writelane_b32 v255, s88, 56
	s_mov_b32 s85, 0
	v_mov_b32_e32 v171, v170
	v_readfirstlane_b32 s7, v3
	v_lshlrev_b32_e32 v3, 10, v6
	v_and_b32_e32 v3, 0xfffff800, v3
	v_lshl_add_u32 v3, v7, 7, v3
	v_lshl_or_b32 v3, v5, 6, v3
	v_lshl_add_u32 v176, v8, 1, v3
	v_lshlrev_b32_e32 v3, 10, v9
	v_and_b32_e32 v3, 0xfffff800, v3
	s_mul_i32 s6, s6, s7
	v_lshl_add_u32 v3, v10, 7, v3
	v_and_b32_e32 v5, 1, v9
	s_mul_hi_u32 s6, s7, s6
	v_lshl_or_b32 v3, v5, 6, v3
	v_mov_b32_e32 v172, v170
	v_mov_b32_e32 v173, v170
	s_ashr_i32 s70, s56, 31
	s_ashr_i32 s88, s55, 31
	s_lshr_b32 s89, s48, 4
	v_lshl_add_u64 v[174:175], s[76:77], 0, v[190:191]
	s_ashr_i32 s73, s49, 31
	s_add_i32 s66, s7, s6
	v_mov_b32_e32 v177, v191
	v_lshl_add_u32 v178, v11, 1, v3
	v_mov_b32_e32 v179, v191
	v_add_u32_e32 v241, 0, v12
	v_lshlrev_b32_e32 v242, 2, v2
	v_lshlrev_b32_e32 v190, 1, v4
	s_barrier
	s_branch .LBB0_218

.LBB0_295:
	v_writelane_b32 v255, s72, 58
	s_mul_i32 s0, s72, 3
	s_and_b32 s70, s6, 3
	v_writelane_b32 v255, s83, 59
	s_add_i32 s26, s0, s83
	s_lshr_b32 s71, s5, 6
	s_lshl_b32 s5, s4, 13
	s_lshl_b32 s19, s70, 12
	s_lshl_b32 s0, s26, 12
	s_lshl_b32 s1, s26, 14
	v_readlane_b32 s6, v255, 43
	v_readlane_b32 s7, v255, 44
	s_add_u32 s72, s6, s1
	s_addc_u32 s73, s7, 0
	s_add_i32 s27, s0, 0x1000
	s_cmp_lt_u32 s26, 11
	s_cselect_b64 s[0:1], -1, 0
	s_and_b64 s[6:7], s[0:1], exec
	s_cselect_b32 s6, s27, 0
	s_lshl_b32 s6, s6, 2
	v_readlane_b32 s44, v255, 39
	v_readlane_b32 s45, v255, 40
	s_add_u32 s82, s44, s6
	s_addc_u32 s83, s45, 0
	s_add_u32 s85, s34, 0x930000
	s_addc_u32 s88, s35, 0
	s_cmp_eq_u32 s26, 5
	s_cselect_b64 s[6:7], -1, 0
	s_add_i32 m0, s61, 0x18000
	v_lshl_add_u64 v[2:3], v[2:3], 0, s[64:65]
	global_load_lds_dwordx4 v[2:3], off
	s_add_i32 m0, s61, 0x1a000
	s_add_u32 s26, s8, s14
	v_mov_b32_e32 v203, v191
	v_lshl_add_u64 v[2:3], v[4:5], 0, s[64:65]
	s_addc_u32 s27, s9, s15
	s_add_i32 s89, s61, 0x8000
	v_mov_b32_e32 v205, v191
	global_load_lds_dwordx4 v[2:3], off
	v_lshl_add_u64 v[2:3], s[26:27], 0, v[202:203]
	s_mov_b32 m0, s89
	s_add_i32 s91, s61, 0xa000
	global_load_lds_dwordx4 v[2:3], off
	v_lshl_add_u64 v[2:3], s[26:27], 0, v[204:205]
	s_mov_b32 m0, s91
	v_bfe_u32 v1, v196, 4, 2
	global_load_lds_dwordx4 v[2:3], off
	s_add_i32 m0, s61, 0x1c000
	v_lshl_add_u64 v[2:3], v[6:7], 0, s[64:65]
	global_load_lds_dwordx4 v[2:3], off
	v_lshl_add_u64 v[2:3], v[8:9], 0, s[64:65]
	s_add_i32 m0, s61, 0x1e000
	v_lshlrev_b32_e32 v5, 4, v1
	global_load_lds_dwordx4 v[2:3], off
	s_cmp_lg_u32 s4, 1
	s_cbranch_scc1 .Lpro_s
	s_barrier
.Lpro_s:
	s_waitcnt vmcnt(8)
	s_barrier
	v_and_b32_e32 v3, 15, v196
	v_lshlrev_b32_e32 v6, 2, v196
	v_lshl_or_b32 v2, s4, 6, v3
	v_lshl_or_b32 v3, v3, 6, v5
	v_and_b32_e32 v6, 32, v6
	v_bitop3_b32 v7, v3, s5, v6 bitop3:0xde
	s_and_b64 s[4:5], s[12:13], exec
	s_cselect_b32 s54, 7, 15
	s_cmpk_lt_u32 s18, 0x100
	v_bitop3_b32 v197, s19, v3, v6 bitop3:0xf6
	s_cselect_b64 s[18:19], -1, 0
	s_ashr_i32 s96, s56, 31
	s_ashr_i32 s97, s55, 31
	s_cmp_lg_u64 s[34:35], 0
	s_cselect_b64 s[26:27], -1, 0
	s_waitcnt vmcnt(6)
	v_ashrrev_i32_e32 v3, 31, v2
	s_and_b64 s[26:27], s[0:1], s[26:27]
	v_readlane_b32 s0, v255, 19
	v_lshlrev_b32_e32 v4, 3, v1
	v_lshlrev_b64 v[208:209], 6, v[2:3]
	v_readlane_b32 s1, v255, 20
	s_mov_b32 s93, 0
	v_or_b32_e32 v208, v208, v4
	v_cmp_eq_u32_e64 s[4:5], 2, v1
	v_or_b32_e32 v199, v2, v5
	s_and_b64 s[80:81], s[6:7], s[0:1]
	v_lshl_or_b32 v220, s70, 6, v4
	s_add_u32 s94, s71, -2
	v_add_u32_e32 v221, 0, v7
	s_barrier
	s_branch .LBB0_298

.LBB0_456:
	s_and_b64 s[4:5], s[4:5], exec
	s_movk_i32 s4, 0x400
	s_cselect_b32 s12, s4, 0xb00
	s_mov_b32 s4, 0x8800
	s_cselect_b32 s37, 8, 22
	s_cselect_b32 s18, 0x5800, s4
	s_and_b64 s[4:5], s[14:15], exec
	s_cselect_b32 s4, 0, s18
	s_lshl_b32 s4, s4, 2
	s_add_u32 s43, s85, s4
	s_addc_u32 s52, s88, 0
	s_and_b32 s4, s16, 3
	s_add_i32 m0, s29, 0x18000
	v_lshl_add_u64 v[2:3], v[2:3], 0, s[64:65]
	s_lshl_b32 s14, s17, 13
	s_lshl_b32 s18, s4, 5
	s_lshl_b32 s15, s4, 12
	global_load_lds_dwordx4 v[2:3], off
	s_add_i32 m0, s29, 0x1a000
	s_add_u32 s4, s50, 0x8000
	v_mov_b32_e32 v147, v191
	v_lshl_add_u64 v[2:3], v[4:5], 0, s[64:65]
	s_addc_u32 s5, s51, 0
	s_add_i32 s53, s29, 0x8000
	v_mov_b32_e32 v151, v191
	global_load_lds_dwordx4 v[2:3], off
	v_lshl_add_u64 v[2:3], s[4:5], 0, v[146:147]
	s_mov_b32 m0, s53
	s_add_i32 s54, s29, 0xa000
	global_load_lds_dwordx4 v[2:3], off
	v_lshl_add_u64 v[2:3], s[4:5], 0, v[150:151]
	s_add_u32 s4, s0, 0x40080
	s_mov_b32 m0, s54
	s_addc_u32 s5, s1, 0
	global_load_lds_dwordx4 v[2:3], off
	s_add_i32 m0, s29, 0x1c000
	v_lshl_add_u64 v[2:3], s[4:5], 0, v[148:149]
	global_load_lds_dwordx4 v[2:3], off
	v_lshl_add_u64 v[2:3], s[4:5], 0, v[152:153]
	s_add_i32 m0, s29, 0x1e000
	v_bfe_u32 v4, v196, 4, 2
	global_load_lds_dwordx4 v[2:3], off
	s_cmp_lg_u32 s17, 1
	s_cbranch_scc1 .Lpro_p
	s_barrier
.Lpro_p:
	s_waitcnt vmcnt(8)
	s_barrier
	v_and_b32_e32 v3, 15, v196
	v_lshlrev_b32_e32 v2, 3, v4
	v_lshlrev_b32_e32 v4, 4, v4
	v_lshlrev_b32_e32 v5, 2, v196
	v_lshl_or_b32 v1, s17, 6, v3
	v_lshl_or_b32 v3, v3, 6, v4
	v_and_b32_e32 v5, 32, v5
	s_cmpk_lt_u32 s9, 0x100
	v_bitop3_b32 v13, v3, s14, v5 bitop3:0xde
	v_bitop3_b32 v165, s15, v3, v5 bitop3:0xf6
	s_cselect_b64 s[14:15], -1, 0
	s_abs_i32 s67, s3
	v_cvt_f32_u32_e32 v3, s67
	v_or_b32_e32 v12, s18, v2
	v_lshlrev_b32_e32 v190, 1, v12
	v_lshl_add_u64 v[14:15], s[34:35], 0, v[190:191]
	v_rcp_iflag_f32_e32 v3, v3
	s_mov_b64 s[4:5], 0xbc00000
	v_lshl_add_u64 v[154:155], v[14:15], 0, s[4:5]
	v_mov_b32_e32 v5, v191
	v_mul_f32_e32 v3, 0x4f7ffffe, v3
	v_cvt_u32_f32_e32 v3, v3
	v_lshl_add_u64 v[158:159], s[76:77], 0, v[4:5]
	v_and_b32_e32 v4, 1, v6
	s_sub_i32 s4, 0, s67
	v_readfirstlane_b32 s5, v3
	v_lshlrev_b32_e32 v3, 10, v6
	v_and_b32_e32 v3, 0xfffff800, v3
	v_lshl_add_u32 v3, v7, 7, v3
	v_lshl_or_b32 v3, v4, 6, v3
	v_lshl_add_u32 v160, v8, 1, v3
	v_lshlrev_b32_e32 v3, 10, v9
	v_and_b32_e32 v3, 0xfffff800, v3
	s_waitcnt vmcnt(6)
	s_mul_i32 s4, s4, s5
	v_lshl_add_u32 v3, v10, 7, v3
	v_and_b32_e32 v4, 1, v9
	s_bfe_u32 s62, s16, 0x10001
	s_and_b32 s16, s18, 32
	s_mul_hi_u32 s4, s5, s4
	v_lshl_or_b32 v3, v4, 6, v3
	s_mov_b32 s61, 0
	s_ashr_i32 s63, s56, 31
	s_ashr_i32 s66, s55, 31
	s_mov_b32 s9, s25
	v_lshl_add_u64 v[156:157], s[78:79], 0, v[190:191]
	s_lshr_b32 s69, s2, 4
	s_lshl_b32 s70, s12, 8
	s_ashr_i32 s71, s3, 31
	s_add_i32 s72, s5, s4
	v_mov_b32_e32 v161, v191
	v_lshl_add_u32 v162, v11, 1, v3
	v_mov_b32_e32 v163, v191
	v_add_u32_e32 v167, 0, v13
	v_lshlrev_b32_e32 v171, 2, v12
	s_lshl_b32 s73, s16, 1
	v_lshlrev_b32_e32 v190, 1, v2
	s_barrier
	s_branch .LBB0_459
